# mode-0 LDS-DMA issue moved from right after the barrier to just before the PV phase
# speedup vs baseline: 1.0927x; 1.0106x over previous
; __device__ __forceinline__ void finishSM(f32x16& p0, f32x16& p1, float alpha, float& l_reg, bf16x8& pa0, bf16x8& pa1, bf16x8& pa2, bf16x8& pa3) {
; #pragma unroll
;   for (int r = 0; r < 16; ++r) p1[r] = __builtin_amdgcn_exp2f(p1[r]);
;   float ps = 0;
; #pragma unroll
;   for (int r = 0; r < 16; ++r) ps += p0[r];
; #pragma unroll
;   for (int r = 0; r < 16; ++r) ps += p1[r];
;   { auto rr = __builtin_amdgcn_permlane32_swap(__float_as_uint(ps), __float_as_uint(ps), false, false);
;     ps = __uint_as_float(rr[0]) + __uint_as_float(rr[1]); }
;   l_reg = l_reg * alpha + ps;
;     ...
;   PK4(p0, 0, pa0); PK4(p0, 8, pa1); PK4(p1, 0, pa2); PK4(p1, 8, pa3);
;     ...
; }
; template <int ND0, int DOFF>
; __device__ __forceinline__ void qkt(f32x16& p0, f32x16& p1, const char* Ks, const bf16x8* qr, int r32, int hi) {
;   p0 = f32x16{}; p1 = f32x16{};
; #pragma unroll
;   for (int d0 = 0; d0 < ND0; ++d0) { const int cb = ((d0 + DOFF) * 16 + hi * 8) * 2;
;     bf16x8 b0 = *reinterpret_cast<const bf16x8*>(Ks + KSWZ(r32, cb));
;     bf16x8 b1 = *reinterpret_cast<const bf16x8*>(Ks + KSWZ(32 + r32, cb));
;     p0 = __builtin_amdgcn_mfma_f32_32x32x16_bf16(b0, qr[d0], p0, 0, 0, 0);
;     p1 = __builtin_amdgcn_mfma_f32_32x32x16_bf16(b1, qr[d0], p1, 0, 0, 0); }
; }
; __device__ __forceinline__ int v_st(int k, int c) { const int kk = (k & ~0xC) | ((k & 4) << 1) | ((k & 8) >> 1); return ((kk >> 3) * 4 + (c >> 5)) * 512 + ((kk & 7) * 32 + (c & 31)) * 2; }
; __device__ __forceinline__ int v_rd_base(int lane) { return ((lane & 3) << 3) | (((lane >> 2) & 3) << 6) | (((lane >> 4) & 1) << 5) | (((lane >> 5) & 1) << 8); }
; template <int OFF> __device__ __forceinline__ s16x4 tr_read(int vb) {
;   s16x4 r; asm volatile("ds_read_b64_tr_b16 %0, %1 offset:%2" : "=&v"(r) : "v"(vb), "i"(OFF) : "memory"); return r;
; }
; template <int MODE>
; __device__ __forceinline__ void attn_body(const bf16_t* __restrict__ Qb, const bf16_t* __restrict__ Kh, const bf16_t* __restrict__ Vh, int NT, int krel0,
;                                           char* lds, const float* __restrict__ lutg, const AttnEpi& E) {
;     ...
;   for (int j = 1; j + 1 < NT; j += 2) {
;     __syncthreads();
;     SBAR(); qkt<ND0, DOFF>(pB0, pB1, K_lds + oq, qr, r32, hi);
;     finishSM(pA0, pA1, alA, l_reg, pa0, pa1, pa2, pa3); SBAR();
;     SLOAD(SO, (j + 2) * 64); SBAR();
;     pv_d0(o, vb0 + op, pa0, pa1, pa2, pa3); PSM(pB0, pB1, mnB, alB, j);
.LBB0_79:
	s_mov_b32 s69, s0
	s_waitcnt vmcnt(0) lgkmcnt(0)
	s_barrier
	s_add_i32 s0, s71, 0
	v_add_u32_e32 v70, s0, v214
	ds_read_b128 v[66:69], v70 offset:49152
	ds_read_b128 v[70:73], v70 offset:57344
	v_add_u32_e32 v162, s0, v218
	ds_read_b128 v[230:233], v162 offset:49152
	ds_read_b128 v[234:237], v162 offset:57344
	v_add_u32_e32 v162, s0, v219
	s_waitcnt lgkmcnt(3)
	v_mfma_f32_32x32x16_bf16 v[82:97], v[66:69], v[114:117], 0
	v_exp_f32_e32 v160, v160
	v_exp_f32_e32 v161, v161
	v_exp_f32_e32 v158, v158
	v_exp_f32_e32 v159, v159
	v_exp_f32_e32 v156, v156
	v_exp_f32_e32 v157, v157
	v_exp_f32_e32 v154, v154
	s_waitcnt lgkmcnt(2)
	v_mfma_f32_32x32x16_bf16 v[66:81], v[70:73], v[114:117], 0
	v_exp_f32_e32 v155, v155
	v_exp_f32_e32 v152, v152
	v_exp_f32_e32 v153, v153
	v_exp_f32_e32 v150, v150
	v_exp_f32_e32 v151, v151
	v_exp_f32_e32 v148, v148
	v_exp_f32_e32 v149, v149
	s_waitcnt lgkmcnt(1)
	v_mfma_f32_32x32x16_bf16 v[82:97], v[230:233], v[126:129], v[82:97]
	v_exp_f32_e32 v146, v146
	v_exp_f32_e32 v147, v147
	v_cvt_pk_bf16_f32 v163, v175, v177
	v_cvt_pk_bf16_f32 v229, v172, v174
	s_waitcnt lgkmcnt(0)
	v_mfma_f32_32x32x16_bf16 v[66:81], v[234:237], v[126:129], v[66:81]
	ds_read_b128 v[230:233], v162 offset:49152
	ds_read_b128 v[234:237], v162 offset:57344
	v_add_u32_e32 v162, s0, v216
	s_waitcnt lgkmcnt(1)
	v_mfma_f32_32x32x16_bf16 v[82:97], v[230:233], v[118:121], v[82:97]
	s_waitcnt lgkmcnt(0)
	v_mfma_f32_32x32x16_bf16 v[66:81], v[234:237], v[118:121], v[66:81]
	ds_read_b128 v[230:233], v162 offset:49152
	ds_read_b128 v[234:237], v162 offset:57344
	v_add_u32_e32 v162, s0, v217
	s_waitcnt lgkmcnt(1)
	v_mfma_f32_32x32x16_bf16 v[82:97], v[230:233], v[122:125], v[82:97]
	s_waitcnt lgkmcnt(0)
	v_mfma_f32_32x32x16_bf16 v[66:81], v[234:237], v[122:125], v[66:81]
	ds_read_b128 v[230:233], v162 offset:49152
	ds_read_b128 v[234:237], v162 offset:57344
	v_add_u32_e32 v162, s0, v215
	s_waitcnt lgkmcnt(1)
	v_mfma_f32_32x32x16_bf16 v[82:97], v[230:233], v[110:113], v[82:97]
	s_waitcnt lgkmcnt(0)
	v_mfma_f32_32x32x16_bf16 v[66:81], v[234:237], v[110:113], v[66:81]
	ds_read_b128 v[230:233], v162 offset:49152
	ds_read_b128 v[234:237], v162 offset:57344
	v_add_u32_e32 v162, s0, v220
	s_waitcnt lgkmcnt(1)
	v_mfma_f32_32x32x16_bf16 v[82:97], v[230:233], v[106:109], v[82:97]
	s_waitcnt lgkmcnt(0)
	v_mfma_f32_32x32x16_bf16 v[66:81], v[234:237], v[106:109], v[66:81]
	ds_read_b128 v[230:233], v162 offset:49152
	ds_read_b128 v[234:237], v162 offset:57344
	v_add_u32_e32 v162, s0, v221
	s_waitcnt lgkmcnt(1)
	v_mfma_f32_32x32x16_bf16 v[82:97], v[230:233], v[102:105], v[82:97]
	s_waitcnt lgkmcnt(0)
	v_mfma_f32_32x32x16_bf16 v[66:81], v[234:237], v[102:105], v[66:81]
	ds_read_b128 v[230:233], v162 offset:49152
	ds_read_b128 v[234:237], v162 offset:57344
	v_add_f32_e32 v162, v165, v164
	v_add_f32_e32 v162, v175, v162
	v_add_f32_e32 v162, v177, v162
	v_add_f32_e32 v162, v227, v162
	v_add_f32_e32 v162, v228, v162
	v_add_f32_e32 v162, v176, v162
	v_add_f32_e32 v162, v226, v162
	v_add_f32_e32 v162, v167, v162
	v_add_f32_e32 v162, v169, v162
	v_add_f32_e32 v162, v171, v162
	v_add_f32_e32 v162, v173, v162
	v_add_f32_e32 v162, v168, v162
	v_add_f32_e32 v162, v170, v162
	v_add_f32_e32 v162, v172, v162
	v_add_f32_e32 v162, v174, v162
	v_add_f32_e32 v162, v160, v162
	v_add_f32_e32 v162, v161, v162
	v_add_f32_e32 v162, v158, v162
	v_add_f32_e32 v162, v159, v162
	v_add_f32_e32 v162, v156, v162
	v_add_f32_e32 v162, v157, v162
	v_add_f32_e32 v162, v154, v162
	v_add_f32_e32 v162, v155, v162
	v_add_f32_e32 v162, v152, v162
	v_add_f32_e32 v162, v153, v162
	s_waitcnt lgkmcnt(1)
	v_mfma_f32_32x32x16_bf16 v[82:97], v[230:233], v[98:101], v[82:97]
	v_add_f32_e32 v162, v150, v162
	v_add_f32_e32 v162, v151, v162
	v_add_f32_e32 v162, v148, v162
	v_add_f32_e32 v162, v149, v162
	v_add_f32_e32 v162, v146, v162
	v_add_f32_e32 v223, v147, v162
	v_mov_b32_e32 v224, v223
	s_waitcnt lgkmcnt(0)
	v_mfma_f32_32x32x16_bf16 v[66:81], v[234:237], v[98:101], v[66:81]
	v_cvt_pk_bf16_f32 v162, v164, v165
	v_cvt_pk_bf16_f32 v164, v227, v228
	v_permlane32_swap_b32_e32 v223, v224
	v_cvt_pk_bf16_f32 v165, v176, v226
	v_permlane32_swap_b32_e32 v162, v164
	v_cvt_pk_bf16_f32 v226, v167, v169
	v_cvt_pk_bf16_f32 v227, v171, v173
	v_cvt_pk_bf16_f32 v228, v168, v170
	v_cvt_pk_bf16_f32 v168, v160, v161
	v_cvt_pk_bf16_f32 v169, v158, v159
	v_cvt_pk_bf16_f32 v170, v156, v157
	v_cvt_pk_bf16_f32 v171, v154, v155
	v_cvt_pk_bf16_f32 v172, v152, v153
	v_cvt_pk_bf16_f32 v173, v150, v151
	v_cvt_pk_bf16_f32 v174, v148, v149
	v_cvt_pk_bf16_f32 v175, v146, v147
	v_permlane32_swap_b32_e32 v163, v165
	v_permlane32_swap_b32_e32 v226, v228
	v_permlane32_swap_b32_e32 v227, v229
	v_permlane32_swap_b32_e32 v168, v170
	v_permlane32_swap_b32_e32 v169, v171
	v_permlane32_swap_b32_e32 v172, v174
	v_permlane32_swap_b32_e32 v173, v175
	s_add_i32 m0, s69, s30
	s_nop 0
	global_load_lds_dwordx4 v130, s[26:27]
	s_add_i32 m0, m0, 0x400
	s_nop 0
	global_load_lds_dwordx4 v131, s[26:27]
	s_add_i32 m0, m0, 0xbc00
	s_nop 0
	global_load_lds_dwordx4 v132, s[28:29]
	s_add_i32 m0, m0, 0x400
	s_nop 0
	global_load_lds_dwordx4 v133, s[28:29]
	s_add_u32 s26, s26, 0x90000
	s_addc_u32 s27, s27, 0
	s_add_u32 s28, s28, 0x90000
	s_addc_u32 s29, s29, 0
	v_add_u32_e32 v208, s68, v209
	ds_read_b64_tr_b16 v[230:231], v208 offset:0
	ds_read_b64_tr_b16 v[232:233], v208 offset:0x800
	ds_read_b64_tr_b16 v[234:235], v208 offset:0x1000
	ds_read_b64_tr_b16 v[236:237], v208 offset:0x1800
	ds_read_b64_tr_b16 v[238:239], v208 offset:0x2000
	ds_read_b64_tr_b16 v[240:241], v208 offset:0x2800
	ds_read_b64_tr_b16 v[242:243], v208 offset:0x3000
	ds_read_b64_tr_b16 v[244:245], v208 offset:0x3800
	s_waitcnt lgkmcnt(0)
; #define SBAR() __builtin_amdgcn_sched_barrier(0)
; #define SWRITE(off, i) do { *(bf16x8*)(V_lds + (off) + vst0) = sr_[i].vs0;          \
;     *(bf16x8*)(V_lds + (off) + vst1) = sr_[i].vs1; int kc = sc * 2;               \
;     *(bf16x8*)(K_lds + (off) + KSWZ(sr, kc)) = sr_[i].ks0;                       \
;     *(bf16x8*)(K_lds + (off) + KSWZ(32 + sr, kc)) = sr_[i].ks1; } while (0)
; #define SWAIT() asm volatile("s_waitcnt vmcnt(4)" ::: "memory")
; #define RESC(a) do { if (__any((a) < 1.f)) { if (hi == 0) al_l[r32] = (a); asm volatile("s_waitcnt lgkmcnt(0)" ::: "memory"); \
;     _Pragma("unroll") for (int d = 0; d < 4; ++d) _Pragma("unroll") for (int r = 0; r < 16; ++r) o[d][r] *= al_l[crow(r, hi)]; } } while (0)
; #define PSM(P0, P1, MN, AL, J) partialSM<MODE>(P0, P1, m_reg, MN, AL, relq + 64 * (J), relwmin + 64 * (J), relwmax + 64 * (J), lut)
; template <int MODE>
; __device__ __forceinline__ void partialSM(f32x16& p0, f32x16& p1, float& m_reg, float& mn, float& alpha, int relh, int relw_min, int relw_max, const float* lut) {
;     ...
;     const float mnC = -mn * C;
; #pragma unroll
;     for (int r = 0; r < 16; ++r) p0[r] = fmaf(p0[r], C, mnC);
; #pragma unroll
;     for (int r = 0; r < 16; ++r) p1[r] = fmaf(p1[r], C, mnC);
; #pragma unroll
;     for (int r = 0; r < 16; ++r) p0[r] = __builtin_amdgcn_exp2f(p0[r]);
; template <int MODE>
; __device__ __forceinline__ void attn_body(const bf16_t* __restrict__ Qb, const bf16_t* __restrict__ Kh, const bf16_t* __restrict__ Vh, int NT, int krel0,
;                                           char* lds, const float* __restrict__ lutg, const AttnEpi& E) {
;     ...
;     pv_d0(o, vb0 + op, pa0, pa1, pa2, pa3); PSM(pB0, pB1, mnB, alB, j);
;     SWAIT(); SWRITE(ow, SE);
;     RESC(alB);
;     { const int t = op; op = oq; oq = ow; ow = t; }
;     __syncthreads();
;     SBAR(); qkt<ND0, DOFF>(pA0, pA1, K_lds + oq, qr, r32, hi);
	s_nop 0
	v_mfma_f32_32x32x16_bf16 v[18:33], v[162:165], v[230:233], v[18:33]
	ds_read_b64_tr_b16 v[230:231], v208 offset:0x200
	ds_read_b64_tr_b16 v[232:233], v208 offset:0xa00
	v_mfma_f32_32x32x16_bf16 v[18:33], v[226:229], v[234:237], v[18:33]
	ds_read_b64_tr_b16 v[234:235], v208 offset:0x1200
	ds_read_b64_tr_b16 v[236:237], v208 offset:0x1a00
	v_mfma_f32_32x32x16_bf16 v[18:33], v[168:171], v[238:241], v[18:33]
	ds_read_b64_tr_b16 v[238:239], v208 offset:0x2200
	ds_read_b64_tr_b16 v[240:241], v208 offset:0x2a00
	v_mfma_f32_32x32x16_bf16 v[18:33], v[172:175], v[242:245], v[18:33]
	ds_read_b64_tr_b16 v[242:243], v208 offset:0x3200
	ds_read_b64_tr_b16 v[244:245], v208 offset:0x3a00
	s_waitcnt lgkmcnt(0)
	v_mfma_f32_32x32x16_bf16 v[50:65], v[162:165], v[230:233], v[50:65]
	ds_read_b64_tr_b16 v[230:231], v208 offset:0x400
	ds_read_b64_tr_b16 v[232:233], v208 offset:0xc00
	v_mfma_f32_32x32x16_bf16 v[50:65], v[226:229], v[234:237], v[50:65]
	ds_read_b64_tr_b16 v[234:235], v208 offset:0x1400
	ds_read_b64_tr_b16 v[236:237], v208 offset:0x1c00
	v_mfma_f32_32x32x16_bf16 v[50:65], v[168:171], v[238:241], v[50:65]
	ds_read_b64_tr_b16 v[238:239], v208 offset:0x2400
	ds_read_b64_tr_b16 v[240:241], v208 offset:0x2c00
	v_mfma_f32_32x32x16_bf16 v[50:65], v[172:175], v[242:245], v[50:65]
	ds_read_b64_tr_b16 v[242:243], v208 offset:0x3400
	ds_read_b64_tr_b16 v[244:245], v208 offset:0x3c00
	s_waitcnt lgkmcnt(0)
	v_mfma_f32_32x32x16_bf16 v[34:49], v[162:165], v[230:233], v[34:49]
	ds_read_b64_tr_b16 v[230:231], v208 offset:0x600
	ds_read_b64_tr_b16 v[232:233], v208 offset:0xe00
	v_mfma_f32_32x32x16_bf16 v[34:49], v[226:229], v[234:237], v[34:49]
	ds_read_b64_tr_b16 v[234:235], v208 offset:0x1600
	ds_read_b64_tr_b16 v[236:237], v208 offset:0x1e00
	v_mfma_f32_32x32x16_bf16 v[34:49], v[168:171], v[238:241], v[34:49]
	ds_read_b64_tr_b16 v[238:239], v208 offset:0x2600
	ds_read_b64_tr_b16 v[240:241], v208 offset:0x2e00
	v_mfma_f32_32x32x16_bf16 v[34:49], v[172:175], v[242:245], v[34:49]
	ds_read_b64_tr_b16 v[242:243], v208 offset:0x3600
	ds_read_b64_tr_b16 v[244:245], v208 offset:0x3e00
	s_waitcnt lgkmcnt(0)
	v_mfma_f32_32x32x16_bf16 v[2:17], v[162:165], v[230:233], v[2:17]
	v_mfma_f32_32x32x16_bf16 v[2:17], v[226:229], v[234:237], v[2:17]
	v_mfma_f32_32x32x16_bf16 v[2:17], v[168:171], v[238:241], v[2:17]
	v_mfma_f32_32x32x16_bf16 v[2:17], v[172:175], v[242:245], v[2:17]
	s_add_i32 s72, s69, 0
.LBB0_83:
	v_mov_b32_e32 v226, v166
	v_mul_f32_e32 v170, 0xbe0293ee, v226
	v_fmamk_f32 v82, v82, 0x3e0293ee, v170
	v_fmamk_f32 v83, v83, 0x3e0293ee, v170
	v_fmamk_f32 v84, v84, 0x3e0293ee, v170
	v_fmamk_f32 v85, v85, 0x3e0293ee, v170
	v_fmamk_f32 v86, v86, 0x3e0293ee, v170
	v_fmamk_f32 v87, v87, 0x3e0293ee, v170
	v_fmamk_f32 v88, v88, 0x3e0293ee, v170
	v_fmamk_f32 v89, v89, 0x3e0293ee, v170
	v_fmamk_f32 v90, v90, 0x3e0293ee, v170
	v_fmamk_f32 v91, v91, 0x3e0293ee, v170
	v_fmamk_f32 v92, v92, 0x3e0293ee, v170
	v_fmamk_f32 v93, v93, 0x3e0293ee, v170
	v_fmamk_f32 v94, v94, 0x3e0293ee, v170
	v_fmamk_f32 v95, v95, 0x3e0293ee, v170
	v_fmamk_f32 v96, v96, 0x3e0293ee, v170
	v_fmamk_f32 v97, v97, 0x3e0293ee, v170
	v_fmamk_f32 v171, v66, 0x3e0293ee, v170
	v_fmamk_f32 v172, v67, 0x3e0293ee, v170
	v_fmamk_f32 v173, v68, 0x3e0293ee, v170
	v_fmamk_f32 v174, v69, 0x3e0293ee, v170
	v_fmamk_f32 v175, v70, 0x3e0293ee, v170
	v_fmamk_f32 v176, v71, 0x3e0293ee, v170
	v_fmamk_f32 v177, v72, 0x3e0293ee, v170
	v_fmamk_f32 v227, v73, 0x3e0293ee, v170
	v_fmamk_f32 v228, v74, 0x3e0293ee, v170
	v_fmamk_f32 v229, v75, 0x3e0293ee, v170
	v_fmamk_f32 v230, v76, 0x3e0293ee, v170
	v_fmamk_f32 v231, v77, 0x3e0293ee, v170
	v_fmamk_f32 v232, v78, 0x3e0293ee, v170
	v_fmamk_f32 v233, v79, 0x3e0293ee, v170
	v_fmamk_f32 v234, v80, 0x3e0293ee, v170
	v_fmac_f32_e32 v170, 0x3e0293ee, v81
	v_exp_f32_e32 v235, v82
	v_exp_f32_e32 v236, v83
	v_exp_f32_e32 v237, v84
	v_exp_f32_e32 v238, v85
	v_exp_f32_e32 v239, v86
	v_exp_f32_e32 v240, v87
	v_exp_f32_e32 v241, v88
	v_exp_f32_e32 v242, v89
	v_exp_f32_e32 v243, v90
	v_exp_f32_e32 v244, v91
	v_exp_f32_e32 v245, v92
	v_exp_f32_e32 v246, v93
	v_exp_f32_e32 v247, v94
	v_exp_f32_e32 v248, v95
	v_exp_f32_e32 v249, v96
	v_exp_f32_e32 v250, v97
	s_waitcnt vmcnt(0) lgkmcnt(0)
	s_barrier
	v_add_u32_e32 v70, s72, v214
	ds_read_b128 v[66:69], v70 offset:49152
	ds_read_b128 v[70:73], v70 offset:57344
	v_add_u32_e32 v166, s72, v218
	ds_read_b128 v[162:165], v166 offset:49152
	ds_read_b128 v[166:169], v166 offset:57344
	v_exp_f32_e32 v171, v171
	s_waitcnt lgkmcnt(3)
	v_mfma_f32_32x32x16_bf16 v[82:97], v[66:69], v[114:117], 0
	v_exp_f32_e32 v172, v172
	v_exp_f32_e32 v173, v173
	v_exp_f32_e32 v174, v174
	v_exp_f32_e32 v175, v175
	v_exp_f32_e32 v176, v176
	v_exp_f32_e32 v177, v177
	v_exp_f32_e32 v227, v227
	s_waitcnt lgkmcnt(2)
	v_mfma_f32_32x32x16_bf16 v[66:81], v[70:73], v[114:117], 0
	v_exp_f32_e32 v228, v228
	v_exp_f32_e32 v251, v229
	v_exp_f32_e32 v195, v230
	v_exp_f32_e32 v231, v231
	v_exp_f32_e32 v232, v232
	v_exp_f32_e32 v233, v233
	v_exp_f32_e32 v234, v234
	s_waitcnt lgkmcnt(1)
	v_mfma_f32_32x32x16_bf16 v[82:97], v[162:165], v[126:129], v[82:97]
	v_exp_f32_e32 v194, v170
	v_cvt_pk_bf16_f32 v170, v171, v172
	s_waitcnt lgkmcnt(0)
	v_mfma_f32_32x32x16_bf16 v[66:81], v[166:169], v[126:129], v[66:81]
	v_add_u32_e32 v166, s72, v219
	ds_read_b128 v[162:165], v166 offset:49152
	ds_read_b128 v[166:169], v166 offset:57344
	s_waitcnt lgkmcnt(1)
	v_mfma_f32_32x32x16_bf16 v[82:97], v[162:165], v[118:121], v[82:97]
	s_waitcnt lgkmcnt(0)
	v_mfma_f32_32x32x16_bf16 v[66:81], v[166:169], v[118:121], v[66:81]
	v_add_u32_e32 v166, s72, v216
	ds_read_b128 v[162:165], v166 offset:49152
	ds_read_b128 v[166:169], v166 offset:57344
	s_waitcnt lgkmcnt(1)
; #define SBAR() __builtin_amdgcn_sched_barrier(0)
; __device__ __forceinline__ void finishSM(f32x16& p0, f32x16& p1, float alpha, float& l_reg, bf16x8& pa0, bf16x8& pa1, bf16x8& pa2, bf16x8& pa3) {
; #pragma unroll
;   for (int r = 0; r < 16; ++r) p1[r] = __builtin_amdgcn_exp2f(p1[r]);
;   float ps = 0;
; #pragma unroll
;   for (int r = 0; r < 16; ++r) ps += p0[r];
; #pragma unroll
;   for (int r = 0; r < 16; ++r) ps += p1[r];
;   { auto rr = __builtin_amdgcn_permlane32_swap(__float_as_uint(ps), __float_as_uint(ps), false, false);
;     ps = __uint_as_float(rr[0]) + __uint_as_float(rr[1]); }
;   l_reg = l_reg * alpha + ps;
;     ...
;   PK4(p0, 0, pa0); PK4(p0, 8, pa1); PK4(p1, 0, pa2); PK4(p1, 8, pa3);
;     ...
; }
; template <int ND0, int DOFF>
; __device__ __forceinline__ void qkt(f32x16& p0, f32x16& p1, const char* Ks, const bf16x8* qr, int r32, int hi) {
;   p0 = f32x16{}; p1 = f32x16{};
; #pragma unroll
;   for (int d0 = 0; d0 < ND0; ++d0) { const int cb = ((d0 + DOFF) * 16 + hi * 8) * 2;
;     bf16x8 b0 = *reinterpret_cast<const bf16x8*>(Ks + KSWZ(r32, cb));
;     bf16x8 b1 = *reinterpret_cast<const bf16x8*>(Ks + KSWZ(32 + r32, cb));
;     p0 = __builtin_amdgcn_mfma_f32_32x32x16_bf16(b0, qr[d0], p0, 0, 0, 0);
;     p1 = __builtin_amdgcn_mfma_f32_32x32x16_bf16(b1, qr[d0], p1, 0, 0, 0); }
; }
; __device__ __forceinline__ int v_st(int k, int c) { const int kk = (k & ~0xC) | ((k & 4) << 1) | ((k & 8) >> 1); return ((kk >> 3) * 4 + (c >> 5)) * 512 + ((kk & 7) * 32 + (c & 31)) * 2; }
; __device__ __forceinline__ int v_rd_base(int lane) { return ((lane & 3) << 3) | (((lane >> 2) & 3) << 6) | (((lane >> 4) & 1) << 5) | (((lane >> 5) & 1) << 8); }
; template <int OFF> __device__ __forceinline__ s16x4 tr_read(int vb) {
;   s16x4 r; asm volatile("ds_read_b64_tr_b16 %0, %1 offset:%2" : "=&v"(r) : "v"(vb), "i"(OFF) : "memory"); return r;
; }
; template <int MODE>
; __device__ __forceinline__ void attn_body(const bf16_t* __restrict__ Qb, const bf16_t* __restrict__ Kh, const bf16_t* __restrict__ Vh, int NT, int krel0,
;                                           char* lds, const float* __restrict__ lutg, const AttnEpi& E) {
;     ...
;     SBAR(); qkt<ND0, DOFF>(pA0, pA1, K_lds + oq, qr, r32, hi);
;     finishSM(pB0, pB1, alB, l_reg, pa0, pa1, pa2, pa3); SBAR();
;     if (j + 3 < NT) SLOAD(SE, (j + 3) * 64); SBAR();
;     pv_d0(o, vb0 + op, pa0, pa1, pa2, pa3); PSM(pA0, pA1, mnA, alA, j + 1);
	v_mfma_f32_32x32x16_bf16 v[82:97], v[162:165], v[122:125], v[82:97]
	s_waitcnt lgkmcnt(0)
	v_mfma_f32_32x32x16_bf16 v[66:81], v[166:169], v[122:125], v[66:81]
	v_add_u32_e32 v166, s72, v217
	ds_read_b128 v[162:165], v166 offset:49152
	ds_read_b128 v[166:169], v166 offset:57344
	s_waitcnt lgkmcnt(1)
	v_mfma_f32_32x32x16_bf16 v[82:97], v[162:165], v[110:113], v[82:97]
	s_waitcnt lgkmcnt(0)
	v_mfma_f32_32x32x16_bf16 v[66:81], v[166:169], v[110:113], v[66:81]
	v_add_u32_e32 v166, s72, v215
	ds_read_b128 v[162:165], v166 offset:49152
	ds_read_b128 v[166:169], v166 offset:57344
	s_waitcnt lgkmcnt(1)
	v_mfma_f32_32x32x16_bf16 v[82:97], v[162:165], v[106:109], v[82:97]
	s_waitcnt lgkmcnt(0)
	v_mfma_f32_32x32x16_bf16 v[66:81], v[166:169], v[106:109], v[66:81]
	v_add_u32_e32 v166, s72, v220
	ds_read_b128 v[162:165], v166 offset:49152
	ds_read_b128 v[166:169], v166 offset:57344
	s_waitcnt lgkmcnt(1)
	v_mfma_f32_32x32x16_bf16 v[82:97], v[162:165], v[102:105], v[82:97]
	s_waitcnt lgkmcnt(0)
	v_mfma_f32_32x32x16_bf16 v[66:81], v[166:169], v[102:105], v[66:81]
	v_add_u32_e32 v166, s72, v221
	ds_read_b128 v[162:165], v166 offset:49152
	ds_read_b128 v[166:169], v166 offset:57344
	s_waitcnt lgkmcnt(1)
	v_mfma_f32_32x32x16_bf16 v[82:97], v[162:165], v[98:101], v[82:97]
	v_add_f32_e32 v162, v236, v235
	v_add_f32_e32 v162, v237, v162
	v_add_f32_e32 v162, v238, v162
	v_add_f32_e32 v162, v239, v162
	v_add_f32_e32 v162, v240, v162
	v_add_f32_e32 v162, v241, v162
	v_add_f32_e32 v162, v242, v162
	v_add_f32_e32 v162, v243, v162
	v_add_f32_e32 v162, v244, v162
	v_add_f32_e32 v162, v245, v162
	v_add_f32_e32 v162, v246, v162
	v_add_f32_e32 v162, v247, v162
	v_add_f32_e32 v162, v248, v162
	v_add_f32_e32 v162, v249, v162
	v_add_f32_e32 v162, v250, v162
	v_add_f32_e32 v162, v171, v162
	v_add_f32_e32 v162, v172, v162
	v_add_f32_e32 v162, v173, v162
	v_add_f32_e32 v162, v174, v162
	v_add_f32_e32 v162, v175, v162
	v_add_f32_e32 v162, v176, v162
	v_add_f32_e32 v162, v177, v162
	v_add_f32_e32 v162, v227, v162
	v_add_f32_e32 v162, v228, v162
	v_add_f32_e32 v162, v251, v162
	s_waitcnt lgkmcnt(0)
	v_mfma_f32_32x32x16_bf16 v[66:81], v[166:169], v[98:101], v[66:81]
	v_add_f32_e32 v162, v195, v162
	v_add_f32_e32 v162, v231, v162
	v_add_f32_e32 v162, v232, v162
	v_add_f32_e32 v162, v233, v162
	v_add_f32_e32 v162, v234, v162
	v_add_f32_e32 v229, v194, v162
	v_mov_b32_e32 v230, v229
	v_cvt_pk_bf16_f32 v162, v235, v236
	v_cvt_pk_bf16_f32 v163, v237, v238
	v_cvt_pk_bf16_f32 v164, v239, v240
	v_cvt_pk_bf16_f32 v165, v241, v242
	v_cvt_pk_bf16_f32 v166, v243, v244
	v_cvt_pk_bf16_f32 v167, v245, v246
	v_cvt_pk_bf16_f32 v168, v247, v248
	v_cvt_pk_bf16_f32 v169, v249, v250
	v_cvt_pk_bf16_f32 v171, v173, v174
	v_cvt_pk_bf16_f32 v172, v175, v176
	v_cvt_pk_bf16_f32 v173, v177, v227
	v_cvt_pk_bf16_f32 v174, v228, v251
	v_cvt_pk_bf16_f32 v175, v195, v231
	v_cvt_pk_bf16_f32 v176, v232, v233
	v_cvt_pk_bf16_f32 v177, v234, v194
	v_permlane32_swap_b32_e32 v229, v230
	v_permlane32_swap_b32_e32 v162, v164
	v_permlane32_swap_b32_e32 v163, v165
	v_permlane32_swap_b32_e32 v166, v168
	v_permlane32_swap_b32_e32 v167, v169
	v_permlane32_swap_b32_e32 v170, v172
	v_permlane32_swap_b32_e32 v171, v173
	v_permlane32_swap_b32_e32 v174, v176
	v_permlane32_swap_b32_e32 v175, v177
.LBB0_85:
	s_add_i32 m0, s68, s30
	s_nop 0
	global_load_lds_dwordx4 v130, s[26:27]
	s_add_i32 m0, m0, 0x400
	s_nop 0
	global_load_lds_dwordx4 v131, s[26:27]
	s_add_i32 m0, m0, 0xbc00
	s_nop 0
	global_load_lds_dwordx4 v132, s[28:29]
	s_add_i32 m0, m0, 0x400
	s_nop 0
	global_load_lds_dwordx4 v133, s[28:29]
	s_add_u32 s26, s26, 0x90000
	s_addc_u32 s27, s27, 0
	s_add_u32 s28, s28, 0x90000
	s_addc_u32 s29, s29, 0
	v_add_u32_e32 v194, s71, v209
	ds_read_b64_tr_b16 v[232:233], v194 offset:0
	ds_read_b64_tr_b16 v[234:235], v194 offset:0x800
	ds_read_b64_tr_b16 v[236:237], v194 offset:0x1000
	ds_read_b64_tr_b16 v[238:239], v194 offset:0x1800
	ds_read_b64_tr_b16 v[240:241], v194 offset:0x2000
	ds_read_b64_tr_b16 v[242:243], v194 offset:0x2800
	ds_read_b64_tr_b16 v[244:245], v194 offset:0x3000
	ds_read_b64_tr_b16 v[246:247], v194 offset:0x3800
	s_waitcnt lgkmcnt(0)
	s_nop 0
	v_mfma_f32_32x32x16_bf16 v[18:33], v[162:165], v[232:235], v[18:33]
	ds_read_b64_tr_b16 v[232:233], v194 offset:0x200
	ds_read_b64_tr_b16 v[234:235], v194 offset:0xa00
	v_mfma_f32_32x32x16_bf16 v[18:33], v[166:169], v[236:239], v[18:33]
	ds_read_b64_tr_b16 v[236:237], v194 offset:0x1200
	ds_read_b64_tr_b16 v[238:239], v194 offset:0x1a00
	v_mfma_f32_32x32x16_bf16 v[18:33], v[170:173], v[240:243], v[18:33]
	ds_read_b64_tr_b16 v[240:241], v194 offset:0x2200
	ds_read_b64_tr_b16 v[242:243], v194 offset:0x2a00
	v_mfma_f32_32x32x16_bf16 v[18:33], v[174:177], v[244:247], v[18:33]
	ds_read_b64_tr_b16 v[244:245], v194 offset:0x3200
	ds_read_b64_tr_b16 v[246:247], v194 offset:0x3a00
	s_waitcnt lgkmcnt(0)
	v_mfma_f32_32x32x16_bf16 v[50:65], v[162:165], v[232:235], v[50:65]
	ds_read_b64_tr_b16 v[232:233], v194 offset:0x400
	ds_read_b64_tr_b16 v[234:235], v194 offset:0xc00
	v_mfma_f32_32x32x16_bf16 v[50:65], v[166:169], v[236:239], v[50:65]
	ds_read_b64_tr_b16 v[236:237], v194 offset:0x1400
	ds_read_b64_tr_b16 v[238:239], v194 offset:0x1c00
	v_mfma_f32_32x32x16_bf16 v[50:65], v[170:173], v[240:243], v[50:65]
	ds_read_b64_tr_b16 v[240:241], v194 offset:0x2400
	ds_read_b64_tr_b16 v[242:243], v194 offset:0x2c00
	v_mfma_f32_32x32x16_bf16 v[50:65], v[174:177], v[244:247], v[50:65]
	ds_read_b64_tr_b16 v[244:245], v194 offset:0x3400
	ds_read_b64_tr_b16 v[246:247], v194 offset:0x3c00
	s_waitcnt lgkmcnt(0)
	v_mfma_f32_32x32x16_bf16 v[34:49], v[162:165], v[232:235], v[34:49]
	ds_read_b64_tr_b16 v[232:233], v194 offset:0x600
	ds_read_b64_tr_b16 v[234:235], v194 offset:0xe00
	v_mfma_f32_32x32x16_bf16 v[34:49], v[166:169], v[236:239], v[34:49]
	ds_read_b64_tr_b16 v[236:237], v194 offset:0x1600
	ds_read_b64_tr_b16 v[238:239], v194 offset:0x1e00
	v_mfma_f32_32x32x16_bf16 v[34:49], v[170:173], v[240:243], v[34:49]
	ds_read_b64_tr_b16 v[240:241], v194 offset:0x2600
	ds_read_b64_tr_b16 v[242:243], v194 offset:0x2e00
	v_mfma_f32_32x32x16_bf16 v[34:49], v[174:177], v[244:247], v[34:49]
	ds_read_b64_tr_b16 v[244:245], v194 offset:0x3600
	ds_read_b64_tr_b16 v[246:247], v194 offset:0x3e00
	s_waitcnt lgkmcnt(0)
	v_mfma_f32_32x32x16_bf16 v[2:17], v[162:165], v[232:235], v[2:17]
	v_mfma_f32_32x32x16_bf16 v[2:17], v[166:169], v[236:239], v[2:17]
	v_mfma_f32_32x32x16_bf16 v[2:17], v[170:173], v[240:243], v[2:17]
	v_mfma_f32_32x32x16_bf16 v[2:17], v[174:177], v[244:247], v[2:17]
	s_add_i32 s72, s68, 0
